# R2 router section: hoisted MFMA fragment reads, batched partial-logit reads, permlane16_swap instead of bpermute, fused DPP max
# baseline (speedup 1.0000x reference)
; #define LAS __attribute__((address_space(3)))
; __device__ __forceinline__ void p_r2(const Args& a, LAS unsigned char* lds, volatile LAS unsigned* MISC, int l, int wg, int G, int wave, int lane, int tid) {
;     ...
;             for (int r = 0; r < 2; ++r) {
;                 if (l == 0) load_row4(xin + (size_t)(t0 + r) * D, lane, x[r]);
;                 else { v2u xw[4]; unpack_row_raw(xpre[r], lane, xw);
; #pragma unroll
;                     for (int j = 0; j < 4; ++j) x[r][j] = (f32x4){bf_lo(xw[j].x), bf_hi(xw[j].x), bf_lo(xw[j].y), bf_hi(xw[j].y)}; }
;                 unpack_row_raw(mpre[r], lane, mw[r]); }
;             if (it + 1 < 16) {
; #pragma unroll
;                 for (int r = 0; r < 2; ++r) { load_row_raw(MIX + (size_t)(t0 + 16 + r) * D, lane, mpre[r]); if (l != 0) load_row_raw(xbf + (size_t)(t0 + 16 + r) * D, lane, xpre[r]); } }
; #pragma unroll
;             for (int j = 0; j < 4; ++j) { const f32x4 g1 = *(const LAS f32x4*)(lds + R2_PAR + (0 * 256 + lane + 64 * j) * 16);
; #pragma unroll
;                 for (int r = 0; r < 2; ++r) { const f32x4 mx = (f32x4){bf_lo(mw[r][j].x), bf_hi(mw[r][j].x), bf_lo(mw[r][j].y), bf_hi(mw[r][j].y)}; x[r][j] = ALPHA * x[r][j] + (1.0f + g1) * mx; } }
;             float mean[2], rstd[2];
; #pragma unroll
;             for (int r = 0; r < 2; ++r) ln_stats(x[r], mean[r], rstd[r]);
.LBB0_836:
	v_cndmask_b32_e64 v136, v188, v136, s[44:45]
	v_cndmask_b32_e64 v138, v138, v188, s[44:45]
	v_cndmask_b32_e64 v188, v191, v133, s[44:45]
	v_cndmask_b32_e64 v133, v18, v124, s[44:45]
	v_cndmask_b32_e64 v193, v126, v18, s[44:45]
	v_add_u32_e32 v18, 0, v156
	v_cndmask_b32_e64 v137, v190, v137, s[44:45]
	v_cndmask_b32_e64 v139, v139, v190, s[44:45]
	v_cndmask_b32_e64 v190, v189, v132, s[44:45]
	v_cndmask_b32_e64 v132, v186, v125, s[44:45]
	v_cndmask_b32_e64 v192, v127, v186, s[44:45]
	v_add_u32_e32 v186, 0x14800, v18
	v_cndmask_b32_e64 v194, v187, v121, s[44:45]
	v_cndmask_b32_e64 v195, v19, v120, s[44:45]
	v_cndmask_b32_e64 v187, v123, v187, s[44:45]
	v_cndmask_b32_e64 v196, v122, v19, s[44:45]
	ds_read_b128 v[120:123], v186
	v_lshlrev_b32_e32 v18, 16, v133
	v_and_b32_e32 v19, 0xffff0000, v133
	v_and_b32_e32 v133, 0xffff0000, v137
	v_lshlrev_b32_e32 v126, 16, v136
	s_waitcnt lgkmcnt(0)
	v_pk_add_f32 v[122:123], v[122:123], 1.0 op_sel_hi:[1,0]
	v_pk_add_f32 v[124:125], v[120:121], 1.0 op_sel_hi:[1,0]
	v_lshlrev_b32_e32 v120, 16, v132
	v_and_b32_e32 v121, 0xffff0000, v132
	v_lshlrev_b32_e32 v132, 16, v137
	v_and_b32_e32 v127, 0xffff0000, v136
	v_pk_mul_f32 v[132:133], v[122:123], v[132:133]
	v_cndmask_b32_e64 v191, v135, v191, s[44:45]
	v_cndmask_b32_e64 v189, v134, v189, s[44:45]
	v_pk_mul_f32 v[120:121], v[122:123], v[120:121]
	v_pk_mul_f32 v[18:19], v[124:125], v[18:19]
	v_pk_mul_f32 v[122:123], v[124:125], v[126:127]
	v_pk_fma_f32 v[124:125], v[150:151], s[10:11], v[132:133] op_sel_hi:[1,0,1]
	ds_read_b128 v[132:135], v186 offset:1024
	v_lshlrev_b32_e32 v126, 16, v193
	v_and_b32_e32 v127, 0xffff0000, v193
	v_pk_fma_f32 v[120:121], v[146:147], s[10:11], v[120:121] op_sel_hi:[1,0,1]
	v_pk_fma_f32 v[18:19], v[144:145], s[10:11], v[18:19] op_sel_hi:[1,0,1]
	s_waitcnt lgkmcnt(0)
	v_pk_add_f32 v[134:135], v[134:135], 1.0 op_sel_hi:[1,0]
	v_pk_add_f32 v[136:137], v[132:133], 1.0 op_sel_hi:[1,0]
	v_lshlrev_b32_e32 v132, 16, v192
	v_and_b32_e32 v133, 0xffff0000, v192
	v_pk_mul_f32 v[132:133], v[134:135], v[132:133]
	v_pk_mul_f32 v[126:127], v[136:137], v[126:127]
	v_pk_fma_f32 v[132:133], v[118:119], s[10:11], v[132:133] op_sel_hi:[1,0,1]
	v_pk_fma_f32 v[126:127], v[116:117], s[10:11], v[126:127] op_sel_hi:[1,0,1]
	v_lshlrev_b32_e32 v116, 16, v138
	v_and_b32_e32 v117, 0xffff0000, v138
	v_lshlrev_b32_e32 v118, 16, v139
	v_and_b32_e32 v119, 0xffff0000, v139
	v_pk_mul_f32 v[118:119], v[134:135], v[118:119]
	v_pk_mul_f32 v[116:117], v[136:137], v[116:117]
	ds_read_b128 v[134:137], v186 offset:2048
	v_pk_fma_f32 v[116:117], v[140:141], s[10:11], v[116:117] op_sel_hi:[1,0,1]
	v_lshlrev_b32_e32 v140, 16, v194
	v_and_b32_e32 v141, 0xffff0000, v194
	v_pk_fma_f32 v[122:123], v[148:149], s[10:11], v[122:123] op_sel_hi:[1,0,1]
	s_waitcnt lgkmcnt(0)
	v_pk_add_f32 v[136:137], v[136:137], 1.0 op_sel_hi:[1,0]
	v_pk_add_f32 v[138:139], v[134:135], 1.0 op_sel_hi:[1,0]
	v_lshlrev_b32_e32 v134, 16, v195
	v_and_b32_e32 v135, 0xffff0000, v195
	v_pk_mul_f32 v[134:135], v[138:139], v[134:135]
	v_pk_mul_f32 v[140:141], v[136:137], v[140:141]
	v_pk_fma_f32 v[134:135], v[112:113], s[10:11], v[134:135] op_sel_hi:[1,0,1]
	v_pk_fma_f32 v[114:115], v[114:115], s[10:11], v[140:141] op_sel_hi:[1,0,1]
	v_lshlrev_b32_e32 v112, 16, v190
	v_and_b32_e32 v113, 0xffff0000, v190
	v_lshlrev_b32_e32 v140, 16, v188
	v_and_b32_e32 v141, 0xffff0000, v188
	v_pk_mul_f32 v[138:139], v[138:139], v[112:113]
	v_pk_mul_f32 v[112:113], v[136:137], v[140:141]
	v_pk_fma_f32 v[136:137], v[128:129], s[10:11], v[138:139] op_sel_hi:[1,0,1]
	v_pk_fma_f32 v[112:113], v[130:131], s[10:11], v[112:113] op_sel_hi:[1,0,1]
	ds_read_b128 v[128:131], v186 offset:3072
	v_lshlrev_b32_e32 v138, 16, v196
	v_and_b32_e32 v139, 0xffff0000, v196
	v_lshlrev_b32_e32 v140, 16, v187
	v_and_b32_e32 v141, 0xffff0000, v187
	s_waitcnt lgkmcnt(0)
	v_pk_add_f32 v[128:129], v[128:129], 1.0 op_sel_hi:[1,0]
	v_pk_add_f32 v[130:131], v[130:131], 1.0 op_sel_hi:[1,0]
	v_pk_mul_f32 v[138:139], v[128:129], v[138:139]
	v_pk_mul_f32 v[140:141], v[130:131], v[140:141]
	v_pk_fma_f32 v[146:147], v[104:105], s[10:11], v[138:139] op_sel_hi:[1,0,1]
	v_lshlrev_b32_e32 v104, 16, v189
	v_and_b32_e32 v105, 0xffff0000, v189
	v_lshlrev_b32_e32 v138, 16, v191
	v_and_b32_e32 v139, 0xffff0000, v191
	v_pk_mul_f32 v[128:129], v[128:129], v[104:105]
	v_pk_mul_f32 v[104:105], v[130:131], v[138:139]
	v_pk_fma_f32 v[144:145], v[108:109], s[10:11], v[128:129] op_sel_hi:[1,0,1]
	v_pk_fma_f32 v[104:105], v[110:111], s[10:11], v[104:105] op_sel_hi:[1,0,1]
	v_pk_mov_b32 v[108:109], v[18:19], v[120:121] op_sel:[1,0]
	v_mov_b32_e32 v110, v18
	v_mov_b32_e32 v111, v121
	v_pk_add_f32 v[108:109], v[108:109], v[110:111]
	v_pk_mov_b32 v[110:111], v[126:127], v[132:133] op_sel:[1,0]
	v_mov_b32_e32 v128, v126
	v_mov_b32_e32 v129, v133
	v_pk_add_f32 v[110:111], v[110:111], v[128:129]
	v_pk_fma_f32 v[106:107], v[106:107], s[10:11], v[140:141] op_sel_hi:[1,0,1]
	v_add_f32_e32 v108, v108, v109
	v_pk_add_f32 v[110:111], v[110:111], v[110:111] op_sel:[0,1] op_sel_hi:[1,0]
	v_add_f32_e32 v108, 0, v108
	v_add_f32_e32 v128, v134, v135
	v_add_f32_e32 v130, v114, v115
	v_mov_b32_e32 v109, v146
	v_mov_b32_e32 v111, v147
	v_mov_b32_e32 v129, v106
	v_mov_b32_e32 v131, v107
	v_pk_add_f32 v[108:109], v[108:109], v[110:111]
	v_pk_add_f32 v[110:111], v[128:129], v[130:131]
	v_pk_fma_f32 v[118:119], v[142:143], s[10:11], v[118:119] op_sel_hi:[1,0,1]
	v_pk_add_f32 v[108:109], v[108:109], v[110:111]
	v_mov_b32_e32 v139, v105
	v_add_f32_e32 v108, v108, v109
	s_nop 1
	v_add_f32_dpp v108, v108, v108 quad_perm:[1,0,3,2] row_mask:0xf bank_mask:0xf bound_ctrl:1
	s_nop 1
; __device__ __forceinline__ void ln_stats(const f32x4 (&v)[4], float& mean, float& rstd) {
;     float s = 0.f;
; #pragma unroll
;     for (int j = 0; j < 4; ++j) s += (v[j][0] + v[j][1]) + (v[j][2] + v[j][3]);
;     mean = wave_sum(s) * (1.f / D); float q = 0.f;
; #pragma unroll
;     for (int j = 0; j < 4; ++j) { const f32x4 d = v[j] - mean; q += (d[0] * d[0] + d[1] * d[1]) + (d[2] * d[2] + d[3] * d[3]); }
;     rstd = rsqrtf(wave_sum(q) * (1.f / D) + LN_EPS);
; }
; __device__ __forceinline__ void p_r2(const Args& a, LAS unsigned char* lds, volatile LAS unsigned* MISC, int l, int wg, int G, int wave, int lane, int tid) {
;     ...
;             float mean[2], rstd[2];
; #pragma unroll
;             for (int r = 0; r < 2; ++r) ln_stats(x[r], mean[r], rstd[r]);
	v_add_f32_dpp v108, v108, v108 quad_perm:[2,3,0,1] row_mask:0xf bank_mask:0xf bound_ctrl:1
	s_nop 1
	v_add_f32_dpp v108, v108, v108 row_half_mirror row_mask:0xf bank_mask:0xf bound_ctrl:1
	s_nop 1
	v_add_f32_dpp v108, v108, v108 row_mirror row_mask:0xf bank_mask:0xf bound_ctrl:1
	s_nop 0
	v_readlane_b32 s4, v108, 16
	v_readlane_b32 s9, v108, 48
	v_readlane_b32 s2, v108, 0
	v_readlane_b32 s3, v108, 32
	v_mov_b32_e32 v108, s4
	v_mov_b32_e32 v109, s9
	v_pk_add_f32 v[108:109], s[2:3], v[108:109]
	s_nop 0
	v_add_f32_e32 v138, v108, v109
	v_fmamk_f32 v19, v138, 0xba800000, v19
	v_fmac_f32_e32 v18, 0xba800000, v138
	v_fmamk_f32 v121, v138, 0xba800000, v121
	v_fmac_f32_e32 v120, 0xba800000, v138
	v_pk_mul_f32 v[108:109], v[120:121], v[120:121]
	v_pk_mul_f32 v[110:111], v[18:19], v[18:19]
	v_fmamk_f32 v127, v138, 0xba800000, v127
	v_pk_mov_b32 v[128:129], v[110:111], v[108:109] op_sel:[1,0]
	v_mov_b32_e32 v111, v109
	v_pk_add_f32 v[108:109], v[128:129], v[110:111]
	v_fmac_f32_e32 v126, 0xba800000, v138
	v_fmamk_f32 v133, v138, 0xba800000, v133
	v_fmac_f32_e32 v132, 0xba800000, v138
	v_pk_add_f32 v[108:109], v[108:109], v[108:109] op_sel_hi:[0,1]
	v_pk_mul_f32 v[110:111], v[132:133], v[132:133]
	v_pk_mul_f32 v[128:129], v[126:127], v[126:127]
	v_fmac_f32_e32 v134, 0xba800000, v138
	v_pk_mov_b32 v[130:131], v[128:129], v[110:111] op_sel:[1,0]
	v_mov_b32_e32 v129, v111
	v_fmamk_f32 v135, v138, 0xba800000, v135
	v_fmac_f32_e32 v114, 0xba800000, v138
	v_mul_f32_e32 v108, v134, v134
	v_pk_add_f32 v[110:111], v[130:131], v[128:129]
	v_fmamk_f32 v115, v138, 0xba800000, v115
	v_pk_fma_f32 v[128:129], v[134:135], v[134:135], v[108:109] op_sel_hi:[1,1,0]
	v_mul_f32_e32 v108, v114, v114
	v_pk_add_f32 v[110:111], v[110:111], v[110:111] op_sel_hi:[0,1]
	v_pk_fma_f32 v[130:131], v[114:115], v[114:115], v[108:109] op_sel_hi:[1,1,0]
	v_fmamk_f32 v107, v138, 0xba800000, v107
	v_fmac_f32_e32 v106, 0xba800000, v138
	v_fmamk_f32 v147, v138, 0xba800000, v147
	v_fmac_f32_e32 v146, 0xba800000, v138
	v_mul_f32_e32 v128, v146, v146
	v_mul_f32_e32 v130, v147, v147
	v_mul_f32_e32 v108, v106, v106
	v_mul_f32_e32 v110, v107, v107
	v_pk_add_f32 v[128:129], v[128:129], v[130:131]
	v_pk_add_f32 v[108:109], v[108:109], v[110:111]
	v_pk_mov_b32 v[110:111], v[122:123], v[124:125] op_sel:[1,0]
	v_pk_add_f32 v[108:109], v[128:129], v[108:109]
	v_mov_b32_e32 v128, v122
	v_mov_b32_e32 v129, v125
	v_pk_add_f32 v[110:111], v[110:111], v[128:129]
	v_pk_mov_b32 v[128:129], v[116:117], v[118:119] op_sel:[1,0]
	v_mov_b32_e32 v130, v116
	v_mov_b32_e32 v131, v119
	v_pk_add_f32 v[128:129], v[128:129], v[130:131]
	v_add_f32_e32 v110, v110, v111
	v_pk_add_f32 v[128:129], v[128:129], v[128:129] op_sel:[0,1] op_sel_hi:[1,0]
	v_add_f32_e32 v110, 0, v110
	v_add_f32_e32 v130, v136, v137
	v_add_f32_e32 v138, v112, v113
	v_mov_b32_e32 v111, v144
	v_mov_b32_e32 v129, v145
	v_mov_b32_e32 v131, v104
	v_pk_add_f32 v[110:111], v[110:111], v[128:129]
	v_pk_add_f32 v[128:129], v[130:131], v[138:139]
	v_add_f32_e32 v108, v108, v109
	v_pk_add_f32 v[110:111], v[110:111], v[128:129]
	s_nop 0
	v_add_f32_dpp v108, v108, v108 quad_perm:[1,0,3,2] row_mask:0xf bank_mask:0xf bound_ctrl:1
	v_add_f32_e32 v110, v110, v111
	s_nop 0
	v_add_f32_dpp v108, v108, v108 quad_perm:[2,3,0,1] row_mask:0xf bank_mask:0xf bound_ctrl:1
	v_add_f32_dpp v110, v110, v110 quad_perm:[1,0,3,2] row_mask:0xf bank_mask:0xf bound_ctrl:1
	s_nop 0
	v_add_f32_dpp v108, v108, v108 row_half_mirror row_mask:0xf bank_mask:0xf bound_ctrl:1
	v_add_f32_dpp v110, v110, v110 quad_perm:[2,3,0,1] row_mask:0xf bank_mask:0xf bound_ctrl:1
	s_nop 0
	v_add_f32_dpp v108, v108, v108 row_mirror row_mask:0xf bank_mask:0xf bound_ctrl:1
	v_add_f32_dpp v110, v110, v110 row_half_mirror row_mask:0xf bank_mask:0xf bound_ctrl:1
	v_readlane_b32 s4, v108, 16
	v_readlane_b32 s9, v108, 48
	v_add_f32_dpp v110, v110, v110 row_mirror row_mask:0xf bank_mask:0xf bound_ctrl:1
	v_readlane_b32 s2, v108, 0
	v_readlane_b32 s3, v108, 32
	v_mov_b32_e32 v108, s4
	v_mov_b32_e32 v109, s9
	v_readlane_b32 s4, v110, 16
	v_readlane_b32 s9, v110, 48
	v_pk_add_f32 v[108:109], s[2:3], v[108:109]
	v_readlane_b32 s2, v110, 0
	v_readlane_b32 s3, v110, 32
	v_mov_b32_e32 v110, s4
	v_mov_b32_e32 v111, s9
	v_pk_add_f32 v[110:111], s[2:3], v[110:111]
	s_nop 0
	v_add_f32_e32 v140, v110, v111
	v_fmamk_f32 v123, v140, 0xba800000, v123
	v_fmac_f32_e32 v122, 0xba800000, v140
	v_fmamk_f32 v125, v140, 0xba800000, v125
	v_fmac_f32_e32 v124, 0xba800000, v140
	v_pk_mul_f32 v[110:111], v[124:125], v[124:125]
	v_pk_mul_f32 v[128:129], v[122:123], v[122:123]
	v_fmamk_f32 v117, v140, 0xba800000, v117
	v_pk_mov_b32 v[130:131], v[128:129], v[110:111] op_sel:[1,0]
	v_mov_b32_e32 v129, v111
	v_pk_add_f32 v[110:111], v[130:131], v[128:129]
	v_fmac_f32_e32 v116, 0xba800000, v140
	v_fmamk_f32 v119, v140, 0xba800000, v119
	v_fmac_f32_e32 v118, 0xba800000, v140
	v_pk_add_f32 v[110:111], v[110:111], v[110:111] op_sel_hi:[0,1]
	v_pk_mul_f32 v[128:129], v[118:119], v[118:119]
	v_pk_mul_f32 v[130:131], v[116:117], v[116:117]
	v_fmac_f32_e32 v136, 0xba800000, v140
	v_pk_mov_b32 v[138:139], v[130:131], v[128:129] op_sel:[1,0]
	v_mov_b32_e32 v131, v129
	v_fmamk_f32 v137, v140, 0xba800000, v137
	v_fmac_f32_e32 v112, 0xba800000, v140
	v_mul_f32_e32 v110, v136, v136
	v_pk_add_f32 v[128:129], v[138:139], v[130:131]
	v_fmamk_f32 v113, v140, 0xba800000, v113
	v_pk_fma_f32 v[130:131], v[136:137], v[136:137], v[110:111] op_sel_hi:[1,1,0]
	v_mul_f32_e32 v110, v112, v112
	v_pk_add_f32 v[128:129], v[128:129], v[128:129] op_sel_hi:[0,1]
	v_pk_fma_f32 v[138:139], v[112:113], v[112:113], v[110:111] op_sel_hi:[1,1,0]
	v_fmamk_f32 v105, v140, 0xba800000, v105
; #define GAS __attribute__((address_space(1)))
; #define LAS __attribute__((address_space(3)))
; __device__ __forceinline__ unsigned pk2(float lo, float hi) { typedef __bf16 bf2_t __attribute__((ext_vector_type(2))); const f32x2 v = {lo, hi}; return __builtin_bit_cast(unsigned, __builtin_convertvector(v, bf2_t)); }
; __device__ __forceinline__ unsigned dpp_swap1(unsigned v) { return (unsigned)__builtin_amdgcn_update_dpp(0, (int)v, 0xB1, 0xF, 0xF, true); }
; __device__ __forceinline__ void store_row_pk(bf16* rowp, int lane, const v2u (&o)[4]) {
;     const bool odd = (lane & 1) != 0; bf16* p = rowp + 4 * (lane & ~1) + (odd ? 256 : 0);
; #pragma unroll
;     for (int pr = 0; pr < 2; ++pr) { const v2u a = o[2 * pr], b = o[2 * pr + 1], send = odd ? a : b; v2u recv; recv.x = dpp_swap1(send.x); recv.y = dpp_swap1(send.y);
;         const v4u w = odd ? (v4u){recv.x, recv.y, b.x, b.y} : (v4u){a.x, a.y, recv.x, recv.y};
;         *(GAS v4u*)(p + 512 * pr) = w; }
; }
; __device__ __forceinline__ void p_r2(const Args& a, LAS unsigned char* lds, volatile LAS unsigned* MISC, int l, int wg, int G, int wave, int lane, int tid) {
;     ...
; #pragma unroll
;             for (int j = 0; j < 4; ++j) { const f32x4 g = *(const LAS f32x4*)(lds + R2_PAR + (1 * 256 + lane + 64 * j) * 16), bb = *(const LAS f32x4*)(lds + R2_PAR + (2 * 256 + lane + 64 * j) * 16);
; #pragma unroll
;                 for (int r = 0; r < 2; ++r) { x[r][j] = (x[r][j] - mean[r]) * rstd[r] * g + bb; ob[r][j].x = pk2(x[r][j][0], x[r][j][1]); ob[r][j].y = pk2(x[r][j][2], x[r][j][3]); } }
; #pragma unroll
;             for (int r = 0; r < 2; ++r) store_row_pk(X1 + (size_t)(t0 + r) * D, lane, ob[r]);
	v_fmac_f32_e32 v104, 0xba800000, v140
	v_fmamk_f32 v145, v140, 0xba800000, v145
	v_fmac_f32_e32 v144, 0xba800000, v140
	v_mul_f32_e32 v130, v144, v144
	v_mul_f32_e32 v138, v145, v145
	v_mul_f32_e32 v110, v104, v104
	v_mul_f32_e32 v128, v105, v105
	v_pk_add_f32 v[130:131], v[130:131], v[138:139]
	v_pk_add_f32 v[110:111], v[110:111], v[128:129]
	v_mov_b32_e32 v129, v108
	v_pk_add_f32 v[110:111], v[130:131], v[110:111]
	s_nop 0
	v_add_f32_e32 v110, v110, v111
	s_nop 1
	v_add_f32_dpp v110, v110, v110 quad_perm:[1,0,3,2] row_mask:0xf bank_mask:0xf bound_ctrl:1
	s_nop 1
	v_add_f32_dpp v110, v110, v110 quad_perm:[2,3,0,1] row_mask:0xf bank_mask:0xf bound_ctrl:1
	s_nop 1
	v_add_f32_dpp v110, v110, v110 row_half_mirror row_mask:0xf bank_mask:0xf bound_ctrl:1
	s_nop 1
	v_add_f32_dpp v110, v110, v110 row_mirror row_mask:0xf bank_mask:0xf bound_ctrl:1
	s_nop 0
	v_readlane_b32 s4, v110, 16
	v_readlane_b32 s9, v110, 48
	v_readlane_b32 s2, v110, 0
	v_readlane_b32 s3, v110, 32
	v_mov_b32_e32 v110, s4
	v_mov_b32_e32 v111, s9
	v_pk_add_f32 v[110:111], s[2:3], v[110:111]
	s_mov_b32 s2, 0x3727c5ac
	v_mov_b32_e32 v128, v110
	v_mov_b32_e32 v108, v111
	v_pk_add_f32 v[108:109], v[128:129], v[108:109]
	v_mov_b64_e32 v[142:143], s[2:3]
	v_pk_fma_f32 v[108:109], v[108:109], s[70:71], v[142:143] op_sel_hi:[1,0,0]
	s_ashr_i32 s9, s8, 31
	v_mul_f32_e32 v110, 0x4b800000, v109
	v_cmp_gt_f32_e64 s[54:55], s68, v109
	v_cmp_gt_f32_e32 vcc, s68, v108
	s_lshl_b64 s[2:3], s[8:9], 11
	v_cndmask_b32_e64 v109, v109, v110, s[54:55]
	v_rsq_f32_e32 v109, v109
	s_nop 0
	v_mul_f32_e32 v110, 0x45800000, v109
	v_cndmask_b32_e64 v188, v109, v110, s[54:55]
	v_mul_f32_e32 v109, 0x4b800000, v108
	v_cndmask_b32_e32 v108, v108, v109, vcc
	v_rsq_f32_e32 v108, v108
	v_pk_mul_f32 v[18:19], v[18:19], v[188:189] op_sel_hi:[1,0]
	v_pk_mul_f32 v[120:121], v[120:121], v[188:189] op_sel_hi:[1,0]
	v_mul_f32_e32 v109, 0x45800000, v108
	v_cndmask_b32_e32 v190, v108, v109, vcc
	ds_read_b128 v[108:111], v186 offset:4096
	ds_read_b128 v[148:151], v186 offset:8192
	s_waitcnt lgkmcnt(0)
	v_pk_fma_f32 v[138:139], v[120:121], v[110:111], v[150:151]
	v_pk_fma_f32 v[140:141], v[18:19], v[108:109], v[148:149]
	v_pk_mul_f32 v[18:19], v[122:123], v[190:191] op_sel_hi:[1,0]
	v_pk_mul_f32 v[120:121], v[124:125], v[190:191] op_sel_hi:[1,0]
	v_pk_fma_f32 v[130:131], v[108:109], v[18:19], v[148:149]
	v_pk_fma_f32 v[128:129], v[110:111], v[120:121], v[150:151]
	ds_read_b128 v[108:111], v186 offset:5120
	ds_read_b128 v[120:123], v186 offset:9216
	v_cvt_pk_bf16_f32 v189, v138, v139
	v_cvt_pk_bf16_f32 v191, v130, v131
	v_pk_mul_f32 v[18:19], v[126:127], v[188:189] op_sel_hi:[1,0]
	v_pk_mul_f32 v[124:125], v[132:133], v[188:189] op_sel_hi:[1,0]
	s_waitcnt lgkmcnt(0)
	v_pk_fma_f32 v[126:127], v[18:19], v[108:109], v[120:121]
	v_pk_mul_f32 v[18:19], v[116:117], v[190:191] op_sel_hi:[1,0]
	v_pk_mul_f32 v[116:117], v[118:119], v[190:191] op_sel_hi:[1,0]
	v_pk_fma_f32 v[124:125], v[124:125], v[110:111], v[122:123]
	v_pk_fma_f32 v[118:119], v[110:111], v[116:117], v[122:123]
	v_pk_fma_f32 v[120:121], v[108:109], v[18:19], v[120:121]
	ds_read_b128 v[108:111], v186 offset:6144
	ds_read_b128 v[148:151], v186 offset:10240
	v_pk_mul_f32 v[18:19], v[134:135], v[188:189] op_sel_hi:[1,0]
	v_pk_mul_f32 v[114:115], v[114:115], v[188:189] op_sel_hi:[1,0]
	v_pk_mul_f32 v[112:113], v[112:113], v[190:191] op_sel_hi:[1,0]
	v_cvt_pk_bf16_f32 v187, v140, v141
	s_waitcnt lgkmcnt(0)
	v_pk_fma_f32 v[116:117], v[18:19], v[108:109], v[148:149]
	v_pk_mul_f32 v[18:19], v[136:137], v[190:191] op_sel_hi:[1,0]
	v_pk_fma_f32 v[114:115], v[114:115], v[110:111], v[150:151]
	v_pk_fma_f32 v[110:111], v[110:111], v[112:113], v[150:151]
	v_pk_fma_f32 v[112:113], v[108:109], v[18:19], v[148:149]
	ds_read_b128 v[132:135], v186 offset:7168
	ds_read_b128 v[148:151], v186 offset:11264
	v_cvt_pk_bf16_f32 v193, v126, v127
	v_cvt_pk_bf16_f32 v194, v124, v125
	v_pk_mul_f32 v[18:19], v[146:147], v[188:189] op_sel_hi:[1,0]
	v_pk_mul_f32 v[122:123], v[144:145], v[190:191] op_sel_hi:[1,0]
	v_pk_mul_f32 v[106:107], v[106:107], v[188:189] op_sel_hi:[1,0]
	s_waitcnt lgkmcnt(0)
	v_pk_fma_f32 v[108:109], v[18:19], v[132:133], v[148:149]
	v_pk_mul_f32 v[18:19], v[104:105], v[190:191] op_sel_hi:[1,0]
	v_pk_fma_f32 v[104:105], v[132:133], v[122:123], v[148:149]
	v_cndmask_b32_e64 v132, v189, v194, s[44:45]
	v_cndmask_b32_e64 v133, v187, v193, s[44:45]
	v_pk_fma_f32 v[106:107], v[106:107], v[134:135], v[150:151]
	v_mov_b32_dpp v132, v132 quad_perm:[1,0,3,2] row_mask:0xf bank_mask:0xf bound_ctrl:1
	v_mov_b32_dpp v148, v133 quad_perm:[1,0,3,2] row_mask:0xf bank_mask:0xf bound_ctrl:1
	v_cvt_pk_bf16_f32 v197, v116, v117
	v_cvt_pk_bf16_f32 v202, v114, v115
	v_cvt_pk_bf16_f32 v146, v108, v109
	v_cvt_pk_bf16_f32 v147, v106, v107
	v_pk_fma_f32 v[18:19], v[134:135], v[18:19], v[150:151]
	v_lshl_add_u64 v[122:123], v[160:161], 0, s[2:3]
	v_cndmask_b32_e64 v135, v194, v132, s[44:45]
	v_cndmask_b32_e64 v134, v193, v148, s[44:45]
	v_cndmask_b32_e64 v133, v132, v189, s[44:45]
	v_cndmask_b32_e64 v132, v148, v187, s[44:45]
	global_store_dwordx4 v[122:123], v[132:135], off
	v_cvt_pk_bf16_f32 v192, v128, v129
	v_cvt_pk_bf16_f32 v195, v120, v121
	v_cndmask_b32_e64 v132, v202, v147, s[44:45]
	v_cndmask_b32_e64 v133, v197, v146, s[44:45]
	v_cvt_pk_bf16_f32 v196, v118, v119
	v_mov_b32_dpp v132, v132 quad_perm:[1,0,3,2] row_mask:0xf bank_mask:0xf bound_ctrl:1
	v_mov_b32_dpp v148, v133 quad_perm:[1,0,3,2] row_mask:0xf bank_mask:0xf bound_ctrl:1
	v_cndmask_b32_e64 v135, v147, v132, s[44:45]
	v_cndmask_b32_e64 v134, v146, v148, s[44:45]
	v_cndmask_b32_e64 v133, v132, v202, s[44:45]
	v_cndmask_b32_e64 v132, v148, v197, s[44:45]
; __device__ __forceinline__ void ln_stats(const f32x4 (&v)[4], float& mean, float& rstd) {
;     float s = 0.f;
; #pragma unroll
;     for (int j = 0; j < 4; ++j) s += (v[j][0] + v[j][1]) + (v[j][2] + v[j][3]);
;     mean = wave_sum(s) * (1.f / D); float q = 0.f;
; #pragma unroll
;     for (int j = 0; j < 4; ++j) { const f32x4 d = v[j] - mean; q += (d[0] * d[0] + d[1] * d[1]) + (d[2] * d[2] + d[3] * d[3]); }
;     rstd = rsqrtf(wave_sum(q) * (1.f / D) + LN_EPS);
; }
; __device__ __forceinline__ void p_r2(const Args& a, LAS unsigned char* lds, volatile LAS unsigned* MISC, int l, int wg, int G, int wave, int lane, int tid) {
;     ...
;             for (int r = 0; r < 2; ++r) store_row_pk(X1 + (size_t)(t0 + r) * D, lane, ob[r]);
; #pragma unroll
;             for (int r = 0; r < 2; ++r) ln_stats(x[r], mean[r], rstd[r]);
	s_add_i32 s2, s8, 1
	global_store_dwordx4 v[122:123], v[132:135], off offset:1024
	s_ashr_i32 s3, s2, 31
	s_lshl_b64 s[34:35], s[2:3], 11
	v_cndmask_b32_e64 v132, v192, v196, s[44:45]
	v_cndmask_b32_e64 v133, v191, v195, s[44:45]
	v_cvt_pk_bf16_f32 v136, v112, v113
	v_mov_b32_dpp v132, v132 quad_perm:[1,0,3,2] row_mask:0xf bank_mask:0xf bound_ctrl:1
	v_mov_b32_dpp v146, v133 quad_perm:[1,0,3,2] row_mask:0xf bank_mask:0xf bound_ctrl:1
	v_cvt_pk_bf16_f32 v137, v110, v111
	v_cvt_pk_bf16_f32 v144, v104, v105
	v_cvt_pk_bf16_f32 v145, v18, v19
	v_lshl_add_u64 v[122:123], v[160:161], 0, s[34:35]
	v_cndmask_b32_e64 v135, v196, v132, s[44:45]
	v_cndmask_b32_e64 v134, v195, v146, s[44:45]
	v_cndmask_b32_e64 v133, v132, v192, s[44:45]
	v_cndmask_b32_e64 v132, v146, v191, s[44:45]
	global_store_dwordx4 v[122:123], v[132:135], off
	s_lshl_b64 s[8:9], s[8:9], 10
	s_lshl_b64 s[2:3], s[2:3], 10
	v_cndmask_b32_e64 v132, v137, v145, s[44:45]
	v_cndmask_b32_e64 v133, v136, v144, s[44:45]
	s_nop 0
	v_mov_b32_dpp v132, v132 quad_perm:[1,0,3,2] row_mask:0xf bank_mask:0xf bound_ctrl:1
	v_mov_b32_dpp v146, v133 quad_perm:[1,0,3,2] row_mask:0xf bank_mask:0xf bound_ctrl:1
	v_cndmask_b32_e64 v135, v145, v132, s[44:45]
	v_cndmask_b32_e64 v134, v144, v146, s[44:45]
	v_cndmask_b32_e64 v133, v132, v137, s[44:45]
	v_cndmask_b32_e64 v132, v146, v136, s[44:45]
	global_store_dwordx4 v[122:123], v[132:135], off offset:1024
	v_pk_mov_b32 v[122:123], v[140:141], v[138:139] op_sel:[1,0]
	v_add_f32_e32 v136, v114, v115
	v_mov_b32_e32 v132, v140
	v_mov_b32_e32 v133, v139
	v_pk_add_f32 v[122:123], v[122:123], v[132:133]
	v_pk_mov_b32 v[132:133], v[126:127], v[124:125] op_sel:[1,0]
	v_mov_b32_e32 v134, v126
	v_mov_b32_e32 v135, v125
	v_pk_add_f32 v[132:133], v[132:133], v[134:135]
	v_add_f32_e32 v122, v122, v123
	v_pk_add_f32 v[132:133], v[132:133], v[132:133] op_sel:[0,1] op_sel_hi:[1,0]
	v_add_f32_e32 v122, 0, v122
	v_add_f32_e32 v134, v116, v117
	v_mov_b32_e32 v123, v108
	v_mov_b32_e32 v133, v109
	v_mov_b32_e32 v135, v106
	v_mov_b32_e32 v137, v107
	v_pk_add_f32 v[122:123], v[122:123], v[132:133]
	v_pk_add_f32 v[132:133], v[134:135], v[136:137]
	v_add_f32_e32 v145, v110, v111
	v_pk_add_f32 v[122:123], v[122:123], v[132:133]
	s_nop 0
	v_add_f32_e32 v122, v122, v123
	s_nop 1
	v_add_f32_dpp v122, v122, v122 quad_perm:[1,0,3,2] row_mask:0xf bank_mask:0xf bound_ctrl:1
	s_nop 1
	v_add_f32_dpp v122, v122, v122 quad_perm:[2,3,0,1] row_mask:0xf bank_mask:0xf bound_ctrl:1
	s_nop 1
	v_add_f32_dpp v122, v122, v122 row_half_mirror row_mask:0xf bank_mask:0xf bound_ctrl:1
	s_nop 1
	v_add_f32_dpp v122, v122, v122 row_mirror row_mask:0xf bank_mask:0xf bound_ctrl:1
	s_nop 0
	v_readlane_b32 s4, v122, 16
	v_readlane_b32 s25, v122, 48
	v_readlane_b32 s34, v122, 0
	v_readlane_b32 s35, v122, 32
	v_mov_b32_e32 v122, s4
	v_mov_b32_e32 v123, s25
	v_pk_add_f32 v[122:123], s[34:35], v[122:123]
	s_nop 0
	v_add_f32_e32 v144, v122, v123
	v_fmamk_f32 v141, v144, 0xba800000, v141
	v_fmac_f32_e32 v140, 0xba800000, v144
	v_fmamk_f32 v139, v144, 0xba800000, v139
	v_fmac_f32_e32 v138, 0xba800000, v144
	v_pk_mul_f32 v[122:123], v[138:139], v[138:139]
	v_pk_mul_f32 v[132:133], v[140:141], v[140:141]
	v_fmamk_f32 v127, v144, 0xba800000, v127
	v_pk_mov_b32 v[134:135], v[132:133], v[122:123] op_sel:[1,0]
	v_mov_b32_e32 v133, v123
	v_pk_add_f32 v[122:123], v[134:135], v[132:133]
	v_fmac_f32_e32 v126, 0xba800000, v144
	v_fmamk_f32 v125, v144, 0xba800000, v125
	v_fmac_f32_e32 v124, 0xba800000, v144
	v_pk_add_f32 v[122:123], v[122:123], v[122:123] op_sel_hi:[0,1]
	v_pk_mul_f32 v[132:133], v[124:125], v[124:125]
	v_pk_mul_f32 v[134:135], v[126:127], v[126:127]
	v_fmac_f32_e32 v116, 0xba800000, v144
	v_pk_mov_b32 v[136:137], v[134:135], v[132:133] op_sel:[1,0]
	v_mov_b32_e32 v135, v133
	v_fmamk_f32 v117, v144, 0xba800000, v117
	v_fmac_f32_e32 v114, 0xba800000, v144
	v_mul_f32_e32 v122, v116, v116
	v_pk_add_f32 v[132:133], v[136:137], v[134:135]
	v_fmamk_f32 v115, v144, 0xba800000, v115
	v_pk_fma_f32 v[134:135], v[116:117], v[116:117], v[122:123] op_sel_hi:[1,1,0]
	v_mul_f32_e32 v122, v114, v114
	v_pk_add_f32 v[132:133], v[132:133], v[132:133] op_sel_hi:[0,1]
	v_pk_fma_f32 v[136:137], v[114:115], v[114:115], v[122:123] op_sel_hi:[1,1,0]
	v_fmamk_f32 v107, v144, 0xba800000, v107
	v_fmac_f32_e32 v106, 0xba800000, v144
	v_fmamk_f32 v109, v144, 0xba800000, v109
	v_fmac_f32_e32 v108, 0xba800000, v144
	v_mul_f32_e32 v134, v108, v108
	v_mul_f32_e32 v136, v109, v109
	v_mul_f32_e32 v122, v106, v106
	v_mul_f32_e32 v132, v107, v107
	v_pk_add_f32 v[134:135], v[134:135], v[136:137]
	v_pk_add_f32 v[122:123], v[122:123], v[132:133]
	v_pk_mov_b32 v[132:133], v[130:131], v[128:129] op_sel:[1,0]
	v_pk_add_f32 v[122:123], v[134:135], v[122:123]
	v_mov_b32_e32 v134, v130
	v_mov_b32_e32 v135, v129
	v_pk_add_f32 v[132:133], v[132:133], v[134:135]
	v_pk_mov_b32 v[134:135], v[120:121], v[118:119] op_sel:[1,0]
	v_mov_b32_e32 v136, v120
	v_mov_b32_e32 v137, v119
	v_pk_add_f32 v[134:135], v[134:135], v[136:137]
	v_add_f32_e32 v132, v132, v133
	v_pk_add_f32 v[134:135], v[134:135], v[134:135] op_sel_hi:[0,1]
	v_add_f32_e32 v133, 0, v132
	v_add_f32_e32 v137, v112, v113
	v_mov_b32_e32 v136, v104
	v_mov_b32_e32 v144, v105
	v_mov_b32_e32 v134, v18
	v_mov_b32_e32 v132, v19
	v_pk_add_f32 v[136:137], v[136:137], v[144:145]
	v_pk_add_f32 v[132:133], v[134:135], v[132:133]
	v_add_f32_e32 v122, v122, v123
	v_pk_add_f32 v[132:133], v[136:137], v[132:133]
	s_nop 0
	v_add_f32_dpp v122, v122, v122 quad_perm:[1,0,3,2] row_mask:0xf bank_mask:0xf bound_ctrl:1
	v_add_f32_e32 v132, v132, v133
	s_nop 0
	v_add_f32_dpp v122, v122, v122 quad_perm:[2,3,0,1] row_mask:0xf bank_mask:0xf bound_ctrl:1
; __device__ __forceinline__ unsigned pk4_fp8(float a, float b, float c, float d) { int w = 0; w = __builtin_amdgcn_cvt_pk_fp8_f32(a, b, w, false); w = __builtin_amdgcn_cvt_pk_fp8_f32(c, d, w, true); return (unsigned)w; }
; #define LAS __attribute__((address_space(3)))
; __device__ __forceinline__ unsigned pk4_fp8(float a, float b, float c, float d) { int w = 0; w = __builtin_amdgcn_cvt_pk_fp8_f32(a, b, w, false); w = __builtin_amdgcn_cvt_pk_fp8_f32(c, d, w, true); return (unsigned)w; }
; __device__ __forceinline__ void p_r2(const Args& a, LAS unsigned char* lds, volatile LAS unsigned* MISC, int l, int wg, int G, int wave, int lane, int tid) {
;     ...
;             for (int r = 0; r < 2; ++r) ln_stats(x[r], mean[r], rstd[r]);
; #pragma unroll
;             for (int j = 0; j < 4; ++j) { const f32x4 s1 = *(const LAS f32x4*)(lds + R2_PAR + (3 * 256 + lane + 64 * j) * 16), s0 = *(const LAS f32x4*)(lds + R2_PAR + (4 * 256 + lane + 64 * j) * 16);
; #pragma unroll
;                 for (int r = 0; r < 2; ++r) { u[r][j] = (x[r][j] - mean[r]) * rstd[r] * (1.0f + s1) + s0;
;                     uq[r][j] = pk4_fp8(u[r][j][0] * F8_SA1, u[r][j][1] * F8_SA1, u[r][j][2] * F8_SA1, u[r][j][3] * F8_SA1);
;                     const h16x2 h0 = __builtin_amdgcn_cvt_pkrtz(u[r][j][0], u[r][j][1]), h1 = __builtin_amdgcn_cvt_pkrtz(u[r][j][2], u[r][j][3]);
;                     const h16x2 l0 = __builtin_amdgcn_cvt_pkrtz(u[r][j][0] - (float)h0[0], u[r][j][1] - (float)h0[1]), l1 = __builtin_amdgcn_cvt_pkrtz(u[r][j][2] - (float)h1[0], u[r][j][3] - (float)h1[1]);
;                     const int row = 2 * wave + r, off = row * 2048 + ((((lane >> 1) + 32 * j) ^ (row & 15)) << 4) + 8 * (lane & 1);
;                     *(LAS v2u*)(lds + R2_UH + off) = (v2u){__builtin_bit_cast(unsigned, h0), __builtin_bit_cast(unsigned, h1)};
;                     *(LAS v2u*)(lds + R2_UL + off) = (v2u){__builtin_bit_cast(unsigned, l0), __builtin_bit_cast(unsigned, l1)}; } }
	v_add_f32_dpp v132, v132, v132 quad_perm:[1,0,3,2] row_mask:0xf bank_mask:0xf bound_ctrl:1
	s_nop 0
	v_add_f32_dpp v122, v122, v122 row_half_mirror row_mask:0xf bank_mask:0xf bound_ctrl:1
	v_add_f32_dpp v132, v132, v132 quad_perm:[2,3,0,1] row_mask:0xf bank_mask:0xf bound_ctrl:1
	s_nop 0
	v_add_f32_dpp v122, v122, v122 row_mirror row_mask:0xf bank_mask:0xf bound_ctrl:1
	v_add_f32_dpp v132, v132, v132 row_half_mirror row_mask:0xf bank_mask:0xf bound_ctrl:1
	v_readlane_b32 s4, v122, 16
	v_readlane_b32 s25, v122, 48
	v_add_f32_dpp v132, v132, v132 row_mirror row_mask:0xf bank_mask:0xf bound_ctrl:1
	v_readlane_b32 s34, v122, 0
	v_readlane_b32 s35, v122, 32
	v_mov_b32_e32 v122, s4
	v_mov_b32_e32 v123, s25
	v_readlane_b32 s4, v132, 16
	v_readlane_b32 s25, v132, 48
	v_pk_add_f32 v[122:123], s[34:35], v[122:123]
	v_readlane_b32 s34, v132, 0
	v_readlane_b32 s35, v132, 32
	v_mov_b32_e32 v132, s4
	v_mov_b32_e32 v133, s25
	v_pk_add_f32 v[132:133], s[34:35], v[132:133]
	s_nop 0
	v_add_f32_e32 v146, v132, v133
	v_fmamk_f32 v131, v146, 0xba800000, v131
	v_fmac_f32_e32 v130, 0xba800000, v146
	v_fmamk_f32 v129, v146, 0xba800000, v129
	v_fmac_f32_e32 v128, 0xba800000, v146
	v_pk_mul_f32 v[132:133], v[128:129], v[128:129]
	v_pk_mul_f32 v[134:135], v[130:131], v[130:131]
	v_fmamk_f32 v121, v146, 0xba800000, v121
	v_pk_mov_b32 v[136:137], v[134:135], v[132:133] op_sel:[1,0]
	v_mov_b32_e32 v135, v133
	v_pk_add_f32 v[132:133], v[136:137], v[134:135]
	v_fmac_f32_e32 v120, 0xba800000, v146
	v_fmamk_f32 v119, v146, 0xba800000, v119
	v_fmac_f32_e32 v118, 0xba800000, v146
	v_pk_add_f32 v[132:133], v[132:133], v[132:133] op_sel_hi:[0,1]
	v_pk_mul_f32 v[134:135], v[118:119], v[118:119]
	v_pk_mul_f32 v[136:137], v[120:121], v[120:121]
	v_fmac_f32_e32 v112, 0xba800000, v146
	v_pk_mov_b32 v[144:145], v[136:137], v[134:135] op_sel:[1,0]
	v_mov_b32_e32 v137, v135
	v_fmamk_f32 v113, v146, 0xba800000, v113
	v_fmac_f32_e32 v110, 0xba800000, v146
	v_mul_f32_e32 v132, v112, v112
	v_pk_add_f32 v[134:135], v[144:145], v[136:137]
	v_fmamk_f32 v111, v146, 0xba800000, v111
	v_pk_fma_f32 v[136:137], v[112:113], v[112:113], v[132:133] op_sel_hi:[1,1,0]
	v_mul_f32_e32 v132, v110, v110
	v_pk_add_f32 v[134:135], v[134:135], v[134:135] op_sel_hi:[0,1]
	v_pk_fma_f32 v[144:145], v[110:111], v[110:111], v[132:133] op_sel_hi:[1,1,0]
	v_fmamk_f32 v19, v146, 0xba800000, v19
	v_fmac_f32_e32 v18, 0xba800000, v146
	v_fmamk_f32 v105, v146, 0xba800000, v105
	v_fmac_f32_e32 v104, 0xba800000, v146
	v_mul_f32_e32 v136, v104, v104
	v_mul_f32_e32 v144, v105, v105
	v_mul_f32_e32 v132, v18, v18
	v_mul_f32_e32 v134, v19, v19
	v_pk_add_f32 v[136:137], v[136:137], v[144:145]
	v_pk_add_f32 v[132:133], v[132:133], v[134:135]
	v_mov_b32_e32 v135, v122
	v_pk_add_f32 v[132:133], v[136:137], v[132:133]
	s_nop 0
	v_add_f32_e32 v132, v132, v133
	s_nop 1
	v_add_f32_dpp v132, v132, v132 quad_perm:[1,0,3,2] row_mask:0xf bank_mask:0xf bound_ctrl:1
	s_nop 1
	v_add_f32_dpp v132, v132, v132 quad_perm:[2,3,0,1] row_mask:0xf bank_mask:0xf bound_ctrl:1
	s_nop 1
	v_add_f32_dpp v132, v132, v132 row_half_mirror row_mask:0xf bank_mask:0xf bound_ctrl:1
	s_nop 1
	v_add_f32_dpp v132, v132, v132 row_mirror row_mask:0xf bank_mask:0xf bound_ctrl:1
	s_nop 0
	v_readlane_b32 s4, v132, 16
	v_readlane_b32 s25, v132, 48
	v_readlane_b32 s34, v132, 0
	v_readlane_b32 s35, v132, 32
	v_mov_b32_e32 v132, s4
	v_mov_b32_e32 v133, s25
	v_pk_add_f32 v[132:133], s[34:35], v[132:133]
	s_nop 0
	v_mov_b32_e32 v134, v132
	v_mov_b32_e32 v122, v133
	v_pk_add_f32 v[122:123], v[134:135], v[122:123]
	s_nop 0
	v_pk_fma_f32 v[122:123], v[122:123], s[70:71], v[142:143] op_sel_hi:[1,0,0]
	ds_read_b128 v[134:137], v186 offset:12288
	ds_read_b128 v[142:145], v186 offset:16384
	v_mul_f32_e32 v132, 0x4b800000, v123
	v_cmp_gt_f32_e64 s[54:55], s68, v123
	v_cmp_gt_f32_e32 vcc, s68, v122
	s_waitcnt lgkmcnt(1)
	v_pk_add_f32 v[134:135], v[134:135], 1.0 op_sel_hi:[1,0]
	v_cndmask_b32_e64 v123, v123, v132, s[54:55]
	v_rsq_f32_e32 v123, v123
	v_pk_add_f32 v[136:137], v[136:137], 1.0 op_sel_hi:[1,0]
	v_mul_f32_e32 v132, 0x45800000, v123
	v_cndmask_b32_e64 v132, v123, v132, s[54:55]
	v_mul_f32_e32 v123, 0x4b800000, v122
	v_cndmask_b32_e32 v122, v122, v123, vcc
	v_rsq_f32_e32 v122, v122
	v_pk_mul_f32 v[140:141], v[140:141], v[132:133] op_sel_hi:[1,0]
	v_pk_mul_f32 v[138:139], v[138:139], v[132:133] op_sel_hi:[1,0]
	s_waitcnt lgkmcnt(0)
; __device__ __forceinline__ unsigned pk4_fp8(float a, float b, float c, float d) { int w = 0; w = __builtin_amdgcn_cvt_pk_fp8_f32(a, b, w, false); w = __builtin_amdgcn_cvt_pk_fp8_f32(c, d, w, true); return (unsigned)w; }
; #define LAS __attribute__((address_space(3)))
; __device__ __forceinline__ unsigned pk4_fp8(float a, float b, float c, float d) { int w = 0; w = __builtin_amdgcn_cvt_pk_fp8_f32(a, b, w, false); w = __builtin_amdgcn_cvt_pk_fp8_f32(c, d, w, true); return (unsigned)w; }
; __device__ __forceinline__ void p_r2(const Args& a, LAS unsigned char* lds, volatile LAS unsigned* MISC, int l, int wg, int G, int wave, int lane, int tid) {
;     ...
;             for (int j = 0; j < 4; ++j) { const f32x4 s1 = *(const LAS f32x4*)(lds + R2_PAR + (3 * 256 + lane + 64 * j) * 16), s0 = *(const LAS f32x4*)(lds + R2_PAR + (4 * 256 + lane + 64 * j) * 16);
; #pragma unroll
;                 for (int r = 0; r < 2; ++r) { u[r][j] = (x[r][j] - mean[r]) * rstd[r] * (1.0f + s1) + s0;
;                     uq[r][j] = pk4_fp8(u[r][j][0] * F8_SA1, u[r][j][1] * F8_SA1, u[r][j][2] * F8_SA1, u[r][j][3] * F8_SA1);
;                     const h16x2 h0 = __builtin_amdgcn_cvt_pkrtz(u[r][j][0], u[r][j][1]), h1 = __builtin_amdgcn_cvt_pkrtz(u[r][j][2], u[r][j][3]);
;                     const h16x2 l0 = __builtin_amdgcn_cvt_pkrtz(u[r][j][0] - (float)h0[0], u[r][j][1] - (float)h0[1]), l1 = __builtin_amdgcn_cvt_pkrtz(u[r][j][2] - (float)h1[0], u[r][j][3] - (float)h1[1]);
;                     const int row = 2 * wave + r, off = row * 2048 + ((((lane >> 1) + 32 * j) ^ (row & 15)) << 4) + 8 * (lane & 1);
;                     *(LAS v2u*)(lds + R2_UH + off) = (v2u){__builtin_bit_cast(unsigned, h0), __builtin_bit_cast(unsigned, h1)};
;                     *(LAS v2u*)(lds + R2_UL + off) = (v2u){__builtin_bit_cast(unsigned, l0), __builtin_bit_cast(unsigned, l1)}; } }
	v_pk_fma_f32 v[140:141], v[140:141], v[134:135], v[142:143]
	v_mul_f32_e32 v123, 0x45800000, v122
	v_cndmask_b32_e32 v122, v122, v123, vcc
	v_mul_f32_e32 v133, 4.0, v140
	v_mul_f32_e32 v146, 4.0, v141
	v_mov_b32_e32 v123, v16
	v_cvt_pk_fp8_f32 v123, v133, v146
	v_cvt_pkrtz_f16_f32 v146, v140, v141
	v_cvt_f32_f16_e32 v133, v146
	v_pk_fma_f32 v[138:139], v[138:139], v[136:137], v[144:145]
	v_sub_f32_e32 v133, v140, v133
	v_cvt_f32_f16_sdwa v140, v146 dst_sel:DWORD dst_unused:UNUSED_PAD src0_sel:WORD_1
	v_mul_f32_e32 v147, 4.0, v138
	v_mul_f32_e32 v148, 4.0, v139
	v_cvt_pk_fp8_f32 v123, v147, v148 op_sel:[0,0,1]
	v_cvt_pkrtz_f16_f32 v147, v138, v139
	v_sub_f32_e32 v140, v141, v140
	v_cvt_pkrtz_f16_f32 v140, v133, v140
	v_cvt_f32_f16_e32 v133, v147
	v_pk_mul_f32 v[130:131], v[130:131], v[122:123] op_sel_hi:[1,0]
	v_pk_mul_f32 v[128:129], v[128:129], v[122:123] op_sel_hi:[1,0]
	v_pk_fma_f32 v[130:131], v[134:135], v[130:131], v[142:143]
	v_sub_f32_e32 v133, v138, v133
	v_cvt_f32_f16_sdwa v138, v147 dst_sel:DWORD dst_unused:UNUSED_PAD src0_sel:WORD_1
	v_pk_fma_f32 v[136:137], v[136:137], v[128:129], v[144:145]
	v_mul_f32_e32 v129, 4.0, v130
	v_mov_b32_e32 v128, v16
	v_sub_f32_e32 v138, v139, v138
	v_cvt_pkrtz_f16_f32 v141, v133, v138
	v_mul_f32_e32 v133, 4.0, v131
	v_cvt_pk_fp8_f32 v128, v129, v133
	v_mul_f32_e32 v134, 4.0, v136
	v_mul_f32_e32 v135, 4.0, v137
	ds_write2st64_b64 v172, v[146:147], v[140:141] offset1:64
	v_cvt_pk_fp8_f32 v128, v134, v135 op_sel:[0,0,1]
	v_cvt_pkrtz_f16_f32 v134, v130, v131
	v_cvt_f32_f16_e32 v129, v134
	v_cvt_pkrtz_f16_f32 v135, v136, v137
	v_pk_mul_f32 v[126:127], v[126:127], v[132:133] op_sel_hi:[1,0]
	v_pk_mul_f32 v[124:125], v[124:125], v[132:133] op_sel_hi:[1,0]
	v_sub_f32_e32 v129, v130, v129
	v_cvt_f32_f16_sdwa v130, v134 dst_sel:DWORD dst_unused:UNUSED_PAD src0_sel:WORD_1
	v_pk_mul_f32 v[120:121], v[120:121], v[122:123] op_sel_hi:[1,0]
	v_pk_mul_f32 v[118:119], v[118:119], v[122:123] op_sel_hi:[1,0]
	v_pk_mul_f32 v[112:113], v[112:113], v[122:123] op_sel_hi:[1,0]
	v_sub_f32_e32 v130, v131, v130
	v_cvt_pkrtz_f16_f32 v130, v129, v130
	v_cvt_f32_f16_e32 v129, v135
	v_cvt_f32_f16_sdwa v131, v135 dst_sel:DWORD dst_unused:UNUSED_PAD src0_sel:WORD_1
	v_pk_mul_f32 v[110:111], v[110:111], v[122:123] op_sel_hi:[1,0]
	v_pk_mul_f32 v[104:105], v[104:105], v[122:123] op_sel_hi:[1,0]
	v_sub_f32_e32 v129, v136, v129
	v_sub_f32_e32 v131, v137, v131
	v_cvt_pkrtz_f16_f32 v131, v129, v131
	ds_write2st64_b64 v173, v[134:135], v[130:131] offset1:64
	ds_read_b128 v[134:137], v186 offset:13312
	ds_read_b128 v[138:141], v186 offset:17408
	v_pk_mul_f32 v[18:19], v[18:19], v[122:123] op_sel_hi:[1,0]
	s_waitcnt lgkmcnt(1)
	v_pk_add_f32 v[134:135], v[134:135], 1.0 op_sel_hi:[1,0]
	v_pk_add_f32 v[130:131], v[136:137], 1.0 op_sel_hi:[1,0]
	s_waitcnt lgkmcnt(0)
	v_pk_fma_f32 v[126:127], v[126:127], v[134:135], v[138:139]
	v_pk_fma_f32 v[136:137], v[124:125], v[130:131], v[140:141]
	v_mul_f32_e32 v125, 4.0, v126
	v_mul_f32_e32 v129, 4.0, v127
	v_mov_b32_e32 v124, v16
	v_cvt_pk_fp8_f32 v124, v125, v129
	v_mul_f32_e32 v133, 4.0, v136
	v_mul_f32_e32 v142, 4.0, v137
	v_cvt_pkrtz_f16_f32 v143, v136, v137
	v_cvt_pk_fp8_f32 v124, v133, v142 op_sel:[0,0,1]
	v_cvt_pkrtz_f16_f32 v142, v126, v127
	v_cvt_f32_f16_e32 v125, v142
	v_pk_fma_f32 v[120:121], v[134:135], v[120:121], v[138:139]
	v_pk_fma_f32 v[118:119], v[130:131], v[118:119], v[140:141]
	v_mov_b32_e32 v130, v16
	v_sub_f32_e32 v125, v126, v125
	v_cvt_f32_f16_sdwa v126, v142 dst_sel:DWORD dst_unused:UNUSED_PAD src0_sel:WORD_1
	v_mul_f32_e32 v129, 4.0, v119
	v_pk_mul_f32 v[116:117], v[116:117], v[132:133] op_sel_hi:[1,0]
	v_mov_b32_e32 v131, v16
	v_sub_f32_e32 v126, v127, v126
	v_cvt_pkrtz_f16_f32 v126, v125, v126
	v_cvt_f32_f16_e32 v125, v143
	v_cvt_f32_f16_sdwa v127, v143 dst_sel:DWORD dst_unused:UNUSED_PAD src0_sel:WORD_1
	v_pk_mul_f32 v[114:115], v[114:115], v[132:133] op_sel_hi:[1,0]
	v_pk_mul_f32 v[108:109], v[108:109], v[132:133] op_sel_hi:[1,0]
	v_sub_f32_e32 v125, v136, v125
	v_sub_f32_e32 v127, v137, v127
	v_cvt_pkrtz_f16_f32 v127, v125, v127
	ds_write2st64_b64 v174, v[142:143], v[126:127] offset1:64
	v_mul_f32_e32 v125, 4.0, v120
	v_mul_f32_e32 v126, 4.0, v121
	v_cvt_pk_fp8_f32 v130, v125, v126
	v_cvt_pkrtz_f16_f32 v126, v120, v121
	v_cvt_f32_f16_e32 v125, v126
	v_mul_f32_e32 v127, 4.0, v118
	v_cvt_pk_fp8_f32 v130, v127, v129 op_sel:[0,0,1]
	v_cvt_pkrtz_f16_f32 v127, v118, v119
	v_sub_f32_e32 v120, v120, v125
	v_cvt_f32_f16_sdwa v125, v126 dst_sel:DWORD dst_unused:UNUSED_PAD src0_sel:WORD_1
	v_pk_mul_f32 v[106:107], v[106:107], v[132:133] op_sel_hi:[1,0]
	v_sub_f32_e32 v121, v121, v125
	v_cvt_pkrtz_f16_f32 v120, v120, v121
	v_cvt_f32_f16_e32 v121, v127
	v_sub_f32_e32 v118, v118, v121
	v_cvt_f32_f16_sdwa v121, v127 dst_sel:DWORD dst_unused:UNUSED_PAD src0_sel:WORD_1
	v_sub_f32_e32 v119, v119, v121
	v_cvt_pkrtz_f16_f32 v121, v118, v119
	ds_write2st64_b64 v175, v[126:127], v[120:121] offset1:64
	ds_read_b128 v[118:121], v186 offset:14336
	ds_read_b128 v[134:137], v186 offset:18432
	s_waitcnt lgkmcnt(1)
	v_pk_add_f32 v[118:119], v[118:119], 1.0 op_sel_hi:[1,0]
	s_waitcnt lgkmcnt(0)
; #define GAS __attribute__((address_space(1)))
; #define LAS __attribute__((address_space(3)))
; __device__ __forceinline__ void store_row_q8(unsigned char* rowp, int lane, const unsigned (&d)[4]) {
;     const bool o1 = (lane & 1) != 0, o2 = (lane & 2) != 0;
;     unsigned p[2][2];
; #pragma unroll
;     for (int cc = 0; cc < 2; ++cc) { const unsigned keep = o1 ? d[2 * cc + 1] : d[2 * cc], send = o1 ? d[2 * cc] : d[2 * cc + 1], recv = dpp_swap1(send); p[cc][0] = o1 ? recv : keep; p[cc][1] = o1 ? keep : recv; }
;     const unsigned s0 = o2 ? p[0][0] : p[1][0], s1 = o2 ? p[0][1] : p[1][1], r0 = dpp_swap2(s0), r1 = dpp_swap2(s1);
;     const v4u w = o2 ? (v4u){r0, r1, p[1][0], p[1][1]} : (v4u){p[0][0], p[0][1], r0, r1};
;     *(GAS v4u*)(rowp + 16 * (lane >> 2) + 256 * (lane & 3)) = w;
; }
; __device__ __forceinline__ void p_r2(const Args& a, LAS unsigned char* lds, volatile LAS unsigned* MISC, int l, int wg, int G, int wave, int lane, int tid) {
;     ...
;             for (int j = 0; j < 4; ++j) { const f32x4 s1 = *(const LAS f32x4*)(lds + R2_PAR + (3 * 256 + lane + 64 * j) * 16), s0 = *(const LAS f32x4*)(lds + R2_PAR + (4 * 256 + lane + 64 * j) * 16);
; #pragma unroll
;                 for (int r = 0; r < 2; ++r) { u[r][j] = (x[r][j] - mean[r]) * rstd[r] * (1.0f + s1) + s0;
;                     uq[r][j] = pk4_fp8(u[r][j][0] * F8_SA1, u[r][j][1] * F8_SA1, u[r][j][2] * F8_SA1, u[r][j][3] * F8_SA1);
;                     const h16x2 h0 = __builtin_amdgcn_cvt_pkrtz(u[r][j][0], u[r][j][1]), h1 = __builtin_amdgcn_cvt_pkrtz(u[r][j][2], u[r][j][3]);
;                     const h16x2 l0 = __builtin_amdgcn_cvt_pkrtz(u[r][j][0] - (float)h0[0], u[r][j][1] - (float)h0[1]), l1 = __builtin_amdgcn_cvt_pkrtz(u[r][j][2] - (float)h1[0], u[r][j][3] - (float)h1[1]);
;                     const int row = 2 * wave + r, off = row * 2048 + ((((lane >> 1) + 32 * j) ^ (row & 15)) << 4) + 8 * (lane & 1);
;                     *(LAS v2u*)(lds + R2_UH + off) = (v2u){__builtin_bit_cast(unsigned, h0), __builtin_bit_cast(unsigned, h1)};
;                     *(LAS v2u*)(lds + R2_UL + off) = (v2u){__builtin_bit_cast(unsigned, l0), __builtin_bit_cast(unsigned, l1)}; } }
; #pragma unroll
;             for (int r = 0; r < 2; ++r) store_row_q8(U8 + (size_t)(t0 + r) * D, lane, uq[r]);
;             __syncthreads();
	v_pk_fma_f32 v[116:117], v[116:117], v[118:119], v[134:135]
	v_pk_add_f32 v[120:121], v[120:121], 1.0 op_sel_hi:[1,0]
	v_mul_f32_e32 v125, 4.0, v116
	v_mul_f32_e32 v126, 4.0, v117
	v_cvt_pk_fp8_f32 v131, v125, v126
	v_cvt_pkrtz_f16_f32 v126, v116, v117
	v_cvt_f32_f16_e32 v125, v126
	v_pk_fma_f32 v[114:115], v[114:115], v[120:121], v[136:137]
	v_pk_fma_f32 v[112:113], v[112:113], v[118:119], v[134:135]
	v_mul_f32_e32 v127, 4.0, v114
	v_sub_f32_e32 v116, v116, v125
	v_cvt_f32_f16_sdwa v125, v126 dst_sel:DWORD dst_unused:UNUSED_PAD src0_sel:WORD_1
	v_mul_f32_e32 v129, 4.0, v115
	v_cvt_pk_fp8_f32 v131, v127, v129 op_sel:[0,0,1]
	v_cvt_pkrtz_f16_f32 v127, v114, v115
	v_sub_f32_e32 v117, v117, v125
	v_cvt_pkrtz_f16_f32 v116, v116, v117
	v_cvt_f32_f16_e32 v117, v127
	v_pk_fma_f32 v[110:111], v[110:111], v[120:121], v[136:137]
	v_mov_b32_e32 v120, v16
	v_sub_f32_e32 v114, v114, v117
	v_cvt_f32_f16_sdwa v117, v127 dst_sel:DWORD dst_unused:UNUSED_PAD src0_sel:WORD_1
	v_sub_f32_e32 v115, v115, v117
	v_cvt_pkrtz_f16_f32 v117, v114, v115
	v_mul_f32_e32 v114, 4.0, v112
	v_mul_f32_e32 v115, 4.0, v113
	v_cvt_pk_fp8_f32 v120, v114, v115
	ds_write2st64_b64 v176, v[126:127], v[116:117] offset1:64
	v_mul_f32_e32 v116, 4.0, v110
	v_mul_f32_e32 v117, 4.0, v111
	v_cvt_pkrtz_f16_f32 v114, v112, v113
	v_cvt_pk_fp8_f32 v120, v116, v117 op_sel:[0,0,1]
	v_cvt_f32_f16_e32 v116, v114
	v_cvt_pkrtz_f16_f32 v115, v110, v111
	v_mov_b32_e32 v126, v16
	v_sub_f32_e32 v112, v112, v116
	v_cvt_f32_f16_sdwa v116, v114 dst_sel:DWORD dst_unused:UNUSED_PAD src0_sel:WORD_1
	v_sub_f32_e32 v113, v113, v116
	v_cvt_pkrtz_f16_f32 v112, v112, v113
	v_cvt_f32_f16_e32 v113, v115
	v_sub_f32_e32 v110, v110, v113
	v_cvt_f32_f16_sdwa v113, v115 dst_sel:DWORD dst_unused:UNUSED_PAD src0_sel:WORD_1
	v_sub_f32_e32 v111, v111, v113
	v_cvt_pkrtz_f16_f32 v113, v110, v111
	ds_write2st64_b64 v177, v[114:115], v[112:113] offset1:64
	ds_read_b128 v[110:113], v186 offset:15360
	ds_read_b128 v[114:117], v186 offset:19456
	s_waitcnt lgkmcnt(1)
	v_pk_add_f32 v[110:111], v[110:111], 1.0 op_sel_hi:[1,0]
	s_waitcnt lgkmcnt(0)
	v_pk_fma_f32 v[108:109], v[108:109], v[110:111], v[114:115]
	v_pk_add_f32 v[112:113], v[112:113], 1.0 op_sel_hi:[1,0]
	v_mul_f32_e32 v118, 4.0, v108
	v_mul_f32_e32 v119, 4.0, v109
	v_cvt_pk_fp8_f32 v126, v118, v119
	v_pk_fma_f32 v[106:107], v[106:107], v[112:113], v[116:117]
	v_cvt_pkrtz_f16_f32 v118, v108, v109
	v_mul_f32_e32 v121, 4.0, v106
	v_mul_f32_e32 v125, 4.0, v107
	v_cvt_pk_fp8_f32 v126, v121, v125 op_sel:[0,0,1]
	v_cvt_f32_f16_e32 v121, v118
	v_cvt_pkrtz_f16_f32 v119, v106, v107
	v_pk_fma_f32 v[104:105], v[104:105], v[110:111], v[114:115]
	v_mov_b32_e32 v110, v16
	v_sub_f32_e32 v108, v108, v121
	v_cvt_f32_f16_sdwa v121, v118 dst_sel:DWORD dst_unused:UNUSED_PAD src0_sel:WORD_1
	v_pk_fma_f32 v[18:19], v[18:19], v[112:113], v[116:117]
	v_sub_f32_e32 v109, v109, v121
	v_cvt_pkrtz_f16_f32 v108, v108, v109
	v_cvt_f32_f16_e32 v109, v119
	v_sub_f32_e32 v106, v106, v109
	v_cvt_f32_f16_sdwa v109, v119 dst_sel:DWORD dst_unused:UNUSED_PAD src0_sel:WORD_1
	v_sub_f32_e32 v107, v107, v109
	v_cvt_pkrtz_f16_f32 v109, v106, v107
	v_mul_f32_e32 v106, 4.0, v104
	v_mul_f32_e32 v107, 4.0, v105
	v_cvt_pk_fp8_f32 v110, v106, v107
	ds_write2st64_b64 v178, v[118:119], v[108:109] offset1:64
	v_mul_f32_e32 v108, 4.0, v18
	v_mul_f32_e32 v109, 4.0, v19
	v_cvt_pkrtz_f16_f32 v106, v104, v105
	v_cvt_pk_fp8_f32 v110, v108, v109 op_sel:[0,0,1]
	v_cvt_f32_f16_e32 v108, v106
	v_cvt_pkrtz_f16_f32 v107, v18, v19
	v_sub_f32_e32 v104, v104, v108
	v_cvt_f32_f16_sdwa v108, v106 dst_sel:DWORD dst_unused:UNUSED_PAD src0_sel:WORD_1
	v_sub_f32_e32 v105, v105, v108
	v_cvt_pkrtz_f16_f32 v104, v104, v105
	v_cvt_f32_f16_e32 v105, v107
	v_sub_f32_e32 v18, v18, v105
	v_cvt_f32_f16_sdwa v105, v107 dst_sel:DWORD dst_unused:UNUSED_PAD src0_sel:WORD_1
	v_sub_f32_e32 v19, v19, v105
	v_cvt_pkrtz_f16_f32 v105, v18, v19
	ds_write2st64_b64 v179, v[106:107], v[104:105] offset1:64
	v_cndmask_b32_e64 v18, v123, v124, s[44:45]
	v_cndmask_b32_e64 v104, v131, v126, s[44:45]
	s_nop 0
	v_mov_b32_dpp v18, v18 quad_perm:[1,0,3,2] row_mask:0xf bank_mask:0xf bound_ctrl:1
	v_mov_b32_dpp v104, v104 quad_perm:[1,0,3,2] row_mask:0xf bank_mask:0xf bound_ctrl:1
	v_cndmask_b32_e64 v19, v18, v123, s[44:45]
	v_cndmask_b32_e64 v18, v124, v18, s[44:45]
	v_cndmask_b32_e64 v105, v104, v131, s[44:45]
	v_cndmask_b32_e64 v104, v126, v104, s[44:45]
	v_cndmask_b32_e64 v106, v19, v105, s[46:47]
	v_cndmask_b32_e64 v107, v18, v104, s[46:47]
	s_nop 0
	v_mov_b32_dpp v108, v106 quad_perm:[2,3,0,1] row_mask:0xf bank_mask:0xf bound_ctrl:1
	v_mov_b32_dpp v109, v107 quad_perm:[2,3,0,1] row_mask:0xf bank_mask:0xf bound_ctrl:1
	v_cndmask_b32_e64 v107, v104, v109, s[46:47]
	v_cndmask_b32_e64 v106, v105, v108, s[46:47]
	v_cndmask_b32_e64 v105, v109, v18, s[46:47]
	v_cndmask_b32_e64 v104, v108, v19, s[46:47]
	v_lshl_add_u64 v[18:19], v[164:165], 0, s[8:9]
	global_store_dwordx4 v[18:19], v[104:107], off
	v_cndmask_b32_e64 v18, v128, v130, s[44:45]
	s_nop 0
	v_cndmask_b32_e64 v104, v120, v110, s[44:45]
	v_mov_b32_dpp v18, v18 quad_perm:[1,0,3,2] row_mask:0xf bank_mask:0xf bound_ctrl:1
	v_cndmask_b32_e64 v19, v18, v128, s[44:45]
	v_mov_b32_dpp v104, v104 quad_perm:[1,0,3,2] row_mask:0xf bank_mask:0xf bound_ctrl:1
	v_cndmask_b32_e64 v18, v130, v18, s[44:45]
	v_cndmask_b32_e64 v105, v104, v120, s[44:45]
	v_cndmask_b32_e64 v104, v110, v104, s[44:45]
	v_cndmask_b32_e64 v106, v19, v105, s[46:47]
	v_cndmask_b32_e64 v107, v18, v104, s[46:47]
	s_nop 0
	v_mov_b32_dpp v108, v106 quad_perm:[2,3,0,1] row_mask:0xf bank_mask:0xf bound_ctrl:1
	v_mov_b32_dpp v109, v107 quad_perm:[2,3,0,1] row_mask:0xf bank_mask:0xf bound_ctrl:1
	v_cndmask_b32_e64 v107, v104, v109, s[46:47]
	v_cndmask_b32_e64 v106, v105, v108, s[46:47]
	v_cndmask_b32_e64 v105, v109, v18, s[46:47]
	v_cndmask_b32_e64 v104, v108, v19, s[46:47]
	v_lshl_add_u64 v[18:19], v[164:165], 0, s[2:3]
	global_store_dwordx4 v[18:19], v[104:107], off
	s_waitcnt lgkmcnt(0)
	s_barrier
; #define LAS __attribute__((address_space(3)))
; __device__ __forceinline__ void p_r2(const Args& a, LAS unsigned char* lds, volatile LAS unsigned* MISC, int l, int wg, int G, int wave, int lane, int tid) {
;     ...
;             f32x4 acc[2] = {(f32x4){0.f, 0.f, 0.f, 0.f}, (f32x4){0.f, 0.f, 0.f, 0.f}};
; #pragma unroll
;             for (int s = 0; s < 4; ++s) { const int off = fr * 2048 + (((4 * (4 * wave + s) + fq) ^ fr) << 4);
;                 const f16x8 ah = *(const LAS f16x8*)(lds + R2_UH + off), al = *(const LAS f16x8*)(lds + R2_UL + off);
; #pragma unroll
;                 for (int nt = 0; nt < 2; ++nt) { acc[nt] = __builtin_amdgcn_mfma_f32_16x16x32_f16(ah, bh[s][nt], acc[nt], 0, 0, 0); acc[nt] = __builtin_amdgcn_mfma_f32_16x16x32_f16(ah, bl[s][nt], acc[nt], 0, 0, 0);
;                     acc[nt] = __builtin_amdgcn_mfma_f32_16x16x32_f16(al, bh[s][nt], acc[nt], 0, 0, 0); } }
; #pragma unroll
;             for (int nt = 0; nt < 2; ++nt)
; #pragma unroll
;                 for (int r = 0; r < 4; ++r) PART[(wave * 16 + 4 * fq + r) * 32 + 16 * nt + fr] = acc[nt][r];
;             __syncthreads();
;             float sgm = rbias;
; #pragma unroll
;             for (int w = 0; w < 8; ++w) sgm += PART[(w * 16 + (tid >> 5)) * 32 + (tid & 31)];
;             { const int half = lane >> 5, ee = lane & 31; float lg = sgm;
;               int si[4]; float sv[4];
; #pragma unroll
;               for (int k = 0; k < 4; ++k) { float mx = row16_max(lg); mx = fmaxf(mx, __shfl_xor(mx, 16)); const unsigned long long bal = __ballot(lg == mx);
;                   const unsigned bits = half ? (unsigned)(bal >> 32) : (unsigned)bal; si[k] = __ffs((int)bits) - 1; sv[k] = mx; if (ee == si[k]) lg = -3.0e38f; }
;               const float e1 = ex2((sv[1] - sv[0]) * LOG2E), e2 = ex2((sv[2] - sv[0]) * LOG2E), e3 = ex2((sv[3] - sv[0]) * LOG2E), inv = 1.0f / (1.0f + e1 + e2 + e3);
;               if (ee == 0) { const int t = tb + 2 * wave + half;
;                   *(LAS v4i*)(lds + R2_TOP + (t - 256 * chunk) * 16) = (v4i){si[0], si[1], si[2], si[3]}; *(LAS f32x4*)(lds + R2_TOP + 4096 + (t - 256 * chunk) * 16) = (f32x4){inv, e1 * inv, e2 * inv, e3 * inv};
; #pragma unroll
;                   for (int k = 0; k < 4; ++k) __hip_atomic_fetch_add((LAS unsigned*)(MISC + MW_HIST + si[k]), 1u, __ATOMIC_RELAXED, __HIP_MEMORY_SCOPE_WORKGROUP); } }
	ds_read_b128 v[104:107], v180
	ds_read_b128 v[108:111], v180 offset:32768
	ds_read_b128 v[120:123], v181
	ds_read_b128 v[124:127], v181 offset:32768
	ds_read_b128 v[128:131], v182
	ds_read_b128 v[132:135], v182 offset:32768
	ds_read_b128 v[136:139], v183
	ds_read_b128 v[140:143], v183 offset:32768
	s_waitcnt lgkmcnt(7)
	v_mfma_f32_16x16x32_f16 v[112:115], v[104:107], v[0:3], 0
	v_mfma_f32_16x16x32_f16 v[116:119], v[104:107], v[8:11], 0
	v_mfma_f32_16x16x32_f16 v[112:115], v[104:107], v[4:7], v[112:115]
	v_mfma_f32_16x16x32_f16 v[116:119], v[104:107], v[12:15], v[116:119]
	s_waitcnt lgkmcnt(6)
	v_mfma_f32_16x16x32_f16 v[112:115], v[108:111], v[0:3], v[112:115]
	v_mfma_f32_16x16x32_f16 v[116:119], v[108:111], v[8:11], v[116:119]
	s_waitcnt lgkmcnt(5)
	v_mfma_f32_16x16x32_f16 v[112:115], v[120:123], v[20:23], v[112:115]
	v_mfma_f32_16x16x32_f16 v[116:119], v[120:123], v[28:31], v[116:119]
	v_mfma_f32_16x16x32_f16 v[112:115], v[120:123], v[24:27], v[112:115]
	v_mfma_f32_16x16x32_f16 v[116:119], v[120:123], v[32:35], v[116:119]
	s_waitcnt lgkmcnt(4)
	v_mfma_f32_16x16x32_f16 v[112:115], v[124:127], v[20:23], v[112:115]
	v_mfma_f32_16x16x32_f16 v[116:119], v[124:127], v[28:31], v[116:119]
	s_waitcnt lgkmcnt(3)
	v_mfma_f32_16x16x32_f16 v[112:115], v[128:131], v[36:39], v[112:115]
	v_mfma_f32_16x16x32_f16 v[116:119], v[128:131], v[44:47], v[116:119]
	v_mfma_f32_16x16x32_f16 v[112:115], v[128:131], v[40:43], v[112:115]
	v_mfma_f32_16x16x32_f16 v[116:119], v[128:131], v[48:51], v[116:119]
	s_waitcnt lgkmcnt(2)
	v_mfma_f32_16x16x32_f16 v[112:115], v[132:135], v[36:39], v[112:115]
	v_mfma_f32_16x16x32_f16 v[116:119], v[132:135], v[44:47], v[116:119]
	s_waitcnt lgkmcnt(1)
	v_mfma_f32_16x16x32_f16 v[112:115], v[136:139], v[52:55], v[112:115]
	v_mfma_f32_16x16x32_f16 v[116:119], v[136:139], v[60:63], v[116:119]
	v_mfma_f32_16x16x32_f16 v[112:115], v[136:139], v[56:59], v[112:115]
	v_mfma_f32_16x16x32_f16 v[116:119], v[136:139], v[68:71], v[116:119]
	s_waitcnt lgkmcnt(0)
	v_mfma_f32_16x16x32_f16 v[112:115], v[140:143], v[52:55], v[112:115]
	v_mfma_f32_16x16x32_f16 v[116:119], v[140:143], v[60:63], v[116:119]
	s_nop 7
	ds_write2_b32 v184, v112, v116 offset1:16
	ds_write2_b32 v184, v113, v117 offset0:32 offset1:48
	ds_write2_b32 v184, v114, v118 offset0:64 offset1:80
	ds_write2_b32 v184, v115, v119 offset0:96 offset1:112
	s_waitcnt lgkmcnt(0)
	s_barrier
	ds_read2st64_b32 v[18:19], v65 offset1:8
	ds_read2st64_b32 v[104:105], v65 offset0:16 offset1:24
	ds_read2st64_b32 v[106:107], v65 offset0:32 offset1:40
	ds_read2st64_b32 v[108:109], v65 offset0:48 offset1:56
	s_waitcnt lgkmcnt(3)
	v_add_f32_e32 v18, v167, v18
	v_add_f32_e32 v18, v18, v19
	s_waitcnt lgkmcnt(2)
	v_add_f32_e32 v18, v18, v104
	v_add_f32_e32 v18, v18, v105
	s_waitcnt lgkmcnt(1)
	v_add_f32_e32 v18, v18, v106
	v_add_f32_e32 v18, v18, v107
	s_waitcnt lgkmcnt(0)
	v_add_f32_e32 v18, v18, v108
	v_add_f32_e32 v19, v18, v109
	s_nop 1
	v_max_f32_dpp v18, v19, v19 quad_perm:[1,0,3,2] row_mask:0xf bank_mask:0xf bound_ctrl:1
	s_nop 1
	v_max_f32_dpp v18, v18, v18 quad_perm:[2,3,0,1] row_mask:0xf bank_mask:0xf bound_ctrl:1
	s_nop 1
	v_max_f32_dpp v18, v18, v18 row_half_mirror row_mask:0xf bank_mask:0xf bound_ctrl:1
	s_nop 1
	v_max_f32_dpp v18, v18, v18 row_mirror row_mask:0xf bank_mask:0xf bound_ctrl:1
	v_mov_b32_e32 v110, v18
	s_nop 1
	v_permlane16_swap_b32_e32 v110, v18
	v_max_f32_e32 v18, v18, v110
	v_cmp_eq_f32_e32 vcc, v19, v18
	s_nop 1
	v_lshrrev_b64 v[104:105], v166, vcc
	v_ffbl_b32_e32 v104, v104
	v_cmp_ne_u32_e32 vcc, v67, v104
	s_nop 1
	v_cndmask_b32_e32 v108, v233, v19, vcc
	s_nop 1
	v_max_f32_dpp v19, v108, v108 quad_perm:[1,0,3,2] row_mask:0xf bank_mask:0xf bound_ctrl:1
	s_nop 1
	v_max_f32_dpp v19, v19, v19 quad_perm:[2,3,0,1] row_mask:0xf bank_mask:0xf bound_ctrl:1
	s_nop 1
	v_max_f32_dpp v19, v19, v19 row_half_mirror row_mask:0xf bank_mask:0xf bound_ctrl:1
	s_nop 1
	v_max_f32_dpp v19, v19, v19 row_mirror row_mask:0xf bank_mask:0xf bound_ctrl:1
	v_mov_b32_e32 v110, v19
	s_nop 1
	v_permlane16_swap_b32_e32 v110, v19
	v_max_f32_e32 v19, v19, v110
	v_cmp_eq_f32_e32 vcc, v108, v19
	s_nop 1
	v_lshrrev_b64 v[106:107], v166, vcc
	v_ffbl_b32_e32 v105, v106
	v_cmp_ne_u32_e32 vcc, v67, v105
	s_nop 1
	v_cndmask_b32_e32 v109, v233, v108, vcc
	s_nop 1
	v_max_f32_dpp v108, v109, v109 quad_perm:[1,0,3,2] row_mask:0xf bank_mask:0xf bound_ctrl:1
	s_nop 1
	v_max_f32_dpp v108, v108, v108 quad_perm:[2,3,0,1] row_mask:0xf bank_mask:0xf bound_ctrl:1
	s_nop 1
	v_max_f32_dpp v108, v108, v108 row_half_mirror row_mask:0xf bank_mask:0xf bound_ctrl:1
	s_nop 1
	v_max_f32_dpp v108, v108, v108 row_mirror row_mask:0xf bank_mask:0xf bound_ctrl:1
	v_mov_b32_e32 v110, v108
	s_nop 1
	v_permlane16_swap_b32_e32 v110, v108
	v_max_f32_e32 v108, v108, v110
	v_cmp_eq_f32_e32 vcc, v109, v108
	s_nop 1
	v_lshrrev_b64 v[106:107], v166, vcc
	v_ffbl_b32_e32 v106, v106
	v_cmp_ne_u32_e32 vcc, v67, v106
	s_nop 1
	v_cndmask_b32_e32 v107, v233, v109, vcc
	s_nop 1
	v_max_f32_dpp v109, v107, v107 quad_perm:[1,0,3,2] row_mask:0xf bank_mask:0xf bound_ctrl:1
	s_nop 1
	v_max_f32_dpp v109, v109, v109 quad_perm:[2,3,0,1] row_mask:0xf bank_mask:0xf bound_ctrl:1
	s_nop 1
	v_max_f32_dpp v109, v109, v109 row_half_mirror row_mask:0xf bank_mask:0xf bound_ctrl:1
	s_nop 1
	v_max_f32_dpp v109, v109, v109 row_mirror row_mask:0xf bank_mask:0xf bound_ctrl:1
	v_mov_b32_e32 v110, v109
	s_nop 1
	v_permlane16_swap_b32_e32 v110, v109
	v_max_f32_e32 v109, v109, v110
	v_cmp_eq_f32_e32 vcc, v107, v109
	s_and_saveexec_b64 s[2:3], s[48:49]
	s_cbranch_execz .LBB0_823
	v_sub_f32_e32 v109, v109, v18
	v_sub_f32_e32 v108, v108, v18
	v_sub_f32_e32 v18, v19, v18
	v_lshrrev_b64 v[110:111], v166, vcc
	v_mul_f32_e32 v18, 0x3fb8aa3b, v18
	v_ffbl_b32_e32 v107, v110
	v_mul_f32_e32 v108, 0x3fb8aa3b, v108
	v_exp_f32_e32 v110, v18
	v_mul_f32_e32 v109, 0x3fb8aa3b, v109
	v_exp_f32_e32 v111, v108
	v_exp_f32_e32 v109, v109
	v_add_f32_e32 v18, 1.0, v110
	v_add_f32_e32 v18, v18, v111
	v_add_f32_e32 v18, v18, v109
	v_div_scale_f32 v19, s[8:9], v18, v18, 1.0
	v_rcp_f32_e32 v108, v19
	s_nop 0
	v_fma_f32 v112, -v19, v108, 1.0
	v_fmac_f32_e32 v108, v112, v108
	v_div_scale_f32 v112, vcc, 1.0, v18, 1.0
	v_mul_f32_e32 v113, v112, v108
	v_fma_f32 v114, -v19, v113, v112
	v_fmac_f32_e32 v113, v114, v108
	v_fma_f32 v19, -v19, v113, v112
	v_div_fmas_f32 v19, v19, v108, v113
	v_div_fixup_f32 v108, v19, v18, 1.0
	v_add_u32_e32 v18, 0xfffff000, v185
	ds_write_b128 v18, v[104:107]
	v_pk_mul_f32 v[18:19], v[110:111], v[108:109] op_sel_hi:[1,0]
	v_mul_f32_e32 v111, v109, v108
	v_mov_b32_e32 v109, v18
	v_mov_b32_e32 v110, v19
	ds_write_b128 v185, v[108:111]
	v_lshl_add_u32 v18, v104, 2, s26
	ds_add_u32 v18, v201
	v_lshl_add_u32 v18, v105, 2, s26
	ds_add_u32 v18, v201
	v_lshl_add_u32 v18, v106, 2, s26
	ds_add_u32 v18, v201
	v_lshl_add_u32 v18, v107, 2, s26
	ds_add_u32 v18, v201
	s_branch .LBB0_823
